# v41 plus barrier arrival atomic issued before the invalidate with a counted wait
# baseline (speedup 1.0000x reference)
; __device__ __forceinline__ unsigned xb_ld(unsigned* p)              { return __hip_atomic_load(p, __ATOMIC_RELAXED, __HIP_MEMORY_SCOPE_AGENT); }
; __device__ __forceinline__ unsigned xb_add(unsigned* p, unsigned v) { return __hip_atomic_fetch_add(p, v, __ATOMIC_RELAXED, __HIP_MEMORY_SCOPE_AGENT); }
; #define XB_SPIN(cond, bar) do { unsigned _sp = 0; while (cond) { __builtin_amdgcn_s_sleep(1); \
;     if ((++_sp & 255u) == 0u) { if (xb_ld(&(bar)[XB_TMO])) break; if (_sp > XB_SPIN_CAP) { atomicAdd(&(bar)[XB_TMO], 1u); break; } } } } while (0)
; __device__ __forceinline__ void xcd_barrier(const XcdBarrier& b) {
;     ...
;     if (threadIdx.x == 0) {
;         unsigned* bar = b.bar; asm volatile("" : "+s"(bar));
;         __builtin_amdgcn_s_waitcnt(0);
;         unsigned nloc = b.st[0], nx = b.st[1];
;         if (nloc == 0u) { xcd_barrier_complete(bar, b.x, nloc, nx); b.st[0] = nloc; b.st[1] = nx; }
;         const unsigned old = xb_add(&bar[XB_XSUB(b.x)], 1u);
;         const unsigned gen = old / nloc;
;         if (old + 1u == (gen + 1u) * nloc) {
;             __builtin_amdgcn_fence(__ATOMIC_RELEASE, "agent");
;             asm volatile("s_waitcnt vmcnt(0)" ::: "memory");
;             const unsigned og = xb_add(&bar[XB_TOP], 1u);
;             const unsigned tg = og / nx;
;             if (og + 1u == (tg + 1u) * nx) xb_add(&bar[XB_TOPGEN], 1u);
;             else XB_SPIN(xb_ld(&bar[XB_TOPGEN]) == tg, bar);
;             __builtin_amdgcn_fence(__ATOMIC_ACQUIRE, "agent");
;             asm volatile("s_waitcnt vmcnt(0)" ::: "memory");
;         } else {
;             XB_SPIN(xb_ld(&bar[XB_TOPGEN]) == gen, bar);
.LBB0_822:
	v_readlane_b32 s4, v246, 51
	s_add_u32 s4, s2, s4
	s_addc_u32 s5, s3, 0
	v_mov_b32_e32 v3, s4
	v_add_co_u32_e32 v4, vcc, 0x1000, v3
	v_mov_b32_e32 v3, s5
	s_nop 0
	v_addc_co_u32_e32 v5, vcc, 0, v3, vcc
	flat_atomic_add v4, v[4:5], v210 offset:1024 sc0
	buffer_inv sc1
	v_cvt_f32_u32_e32 v3, v2
	v_sub_u32_e32 v5, 0, v2
	v_rcp_iflag_f32_e32 v3, v3
	s_nop 0
	v_mul_f32_e32 v3, 0x4f7ffffe, v3
	v_cvt_u32_f32_e32 v3, v3
	v_mul_lo_u32 v5, v5, v3
	v_mul_hi_u32 v5, v3, v5
	v_add_u32_e32 v3, v3, v5
	s_waitcnt vmcnt(1) lgkmcnt(0)
	v_mul_hi_u32 v3, v4, v3
	v_mul_lo_u32 v5, v3, v2
	v_sub_u32_e32 v5, v4, v5
	v_cmp_ge_u32_e32 vcc, v5, v2
	v_add_u32_e32 v6, 1, v3
	s_nop 0
	v_cndmask_b32_e32 v3, v3, v6, vcc
	v_sub_u32_e32 v6, v5, v2
	v_cndmask_b32_e32 v5, v5, v6, vcc
	v_cmp_ge_u32_e32 vcc, v5, v2
	v_add_u32_e32 v5, 1, v3
	v_add_u32_e32 v6, 1, v4
	v_cndmask_b32_e32 v3, v3, v5, vcc
	v_mad_u64_u32 v[4:5], s[4:5], v2, v3, v[2:3]
	v_cmp_ne_u32_e32 vcc, v6, v4
	s_and_saveexec_b64 s[4:5], vcc
	s_xor_b64 s[24:25], exec, s[4:5]
	s_cbranch_execz .LBB0_835
	v_mad_u32_u24 v20, v3, v0, v0
	v_mov_b32_e32 v0, s2
	v_add_co_u32_e32 v4, vcc, 0x3000, v0
	v_mov_b32_e32 v0, s3
	s_nop 0
	v_addc_co_u32_e32 v5, vcc, 0, v0, vcc
	flat_load_dword v0, v[4:5] offset:1024 sc1
	s_add_u32 s30, s2, 0x3500
	s_addc_u32 s31, s3, 0
	s_waitcnt vmcnt(0) lgkmcnt(0)
	v_cmp_lt_u32_e32 vcc, v0, v20
	s_and_saveexec_b64 s[26:27], vcc
	s_cbranch_execz .LBB0_834
	s_mov_b32 s4, 1
	s_mov_b64 s[36:37], 0
	s_branch .LBB0_826
